# dense-attention third round as quarter units on the SSD-B blocks (blocks 0..127), two full pair-units per attention block
# speedup vs baseline: 1.0036x; 1.0036x over previous
.Lga_entry_q:
	v_readlane_b32 s40, v254, 33
	s_mov_b32 s93, 1
	s_cmpk_lt_u32 s40, 0x80
	s_cbranch_scc1 .Lga_init
	s_branch .LBB0_979
.Lga_entry:
	s_mov_b32 s93, 0
.Lga_init:
	s_mov_b64 exec, -1
	s_load_dwordx2 s[4:5], s[64:65], 0xf8
	s_mov_b32 s100, 0x3e38aa3b
	s_mov_b32 s101, 0
	v_mov_b32_e32 v86, 0x3e38aa3b
	v_and_b32_e32 v144, 63, v247
	v_lshrrev_b32_e32 v145, 6, v247
	v_and_b32_e32 v146, 15, v144
	v_lshrrev_b32_e32 v147, 4, v144
	v_readfirstlane_b32 s21, v145
	v_bfe_u32 v148, v146, 1, 3
	v_lshlrev_b32_e32 v149, 7, v146
	v_xor_b32_e32 v150, v147, v148
	v_lshl_add_u32 v136, v150, 4, v149
	v_add_u32_e32 v136, 16, v136
	v_xor_b32_e32 v150, 4, v150
	v_lshl_add_u32 v137, v150, 4, v149
	v_add_u32_e32 v137, 16, v137
	v_lshrrev_b32_e32 v151, 1, v147
	v_and_b32_e32 v152, 1, v147
	v_lshlrev_b32_e32 v152, 3, v152
	v_add_u32_e32 v152, v152, v149
	v_add_u32_e32 v152, 0x2010, v152
	v_add_u32_e32 v153, 0, v151
	v_xor_b32_e32 v153, v153, v148
	v_lshl_add_u32 v138, v153, 4, v152
	v_add_u32_e32 v153, 2, v151
	v_xor_b32_e32 v153, v153, v148
	v_lshl_add_u32 v139, v153, 4, v152
	v_add_u32_e32 v153, 4, v151
	v_xor_b32_e32 v153, v153, v148
	v_lshl_add_u32 v140, v153, 4, v152
	v_add_u32_e32 v153, 6, v151
	v_xor_b32_e32 v153, v153, v148
	v_lshl_add_u32 v141, v153, 4, v152
	s_lshl_b32 s0, s21, 3
	v_lshrrev_b32_e32 v153, 3, v144
	v_add_u32_e32 v153, s0, v153
	v_bfe_u32 v154, v153, 1, 3
	v_and_b32_e32 v155, 7, v144
	v_xor_b32_e32 v154, v154, v155
	v_lshlrev_b32_e32 v154, 4, v154
	v_mul_u32_u24_e32 v142, 0x3000, v153
	v_add_u32_e32 v142, v142, v154
	v_mul_u32_u24_e32 v143, 0x9000, v153
	v_add_u32_e32 v143, v143, v154
	s_lshl_b32 s32, s21, 10
	s_add_u32 s32, s32, 16
	s_add_u32 s41, s32, 0x2000
	s_sub_u32 s1, s40, 144
	s_cmp_eq_u32 s93, 0
	s_cbranch_scc1 .Lga_full
	s_lshr_b32 s1, s40, 2
	s_add_u32 s1, s1, 0xe0
	s_bitcmp1_b32 s40, 0
	s_cselect_b32 s101, 6, 10
	s_bfe_u32 s0, s40, 0x10001
	s_lshr_b32 s92, s21, 2
	s_cmp_lg_u32 s92, s0
	s_cselect_b32 s0, 1, 0
	s_or_b32 s101, s101, s0
.Lga_full:
	s_waitcnt lgkmcnt(0)
.Lga_unit:
	v_and_b32_e32 v144, 63, v247
	s_and_b32 s80, s1, 15
	s_bfe_u32 s81, s1, 0x10004
	s_lshr_b32 s43, s1, 5
	s_lshl_b32 s0, s81, 7
	s_add_u32 s0, s0, 0x900
	s_add_u32 s6, s4, 0x9f00000
	s_addc_u32 s7, s5, 0
	s_add_u32 s6, s6, s0
	s_addc_u32 s7, s7, 0
	s_mul_i32 s0, s43, 0x1800000
	s_add_u32 s96, s6, s0
	s_addc_u32 s97, s7, 0
	s_mul_i32 s0, s43, 0x300000
	s_add_u32 s6, s6, s0
	s_addc_u32 s7, s7, 0
	s_add_u32 s6, s6, 0xc000000
	s_addc_u32 s7, s7, 0
	s_lshl_b32 s0, s81, 6
	s_add_u32 s0, s0, 0x180
	s_mul_i32 s0, s0, 0x9000
	s_add_u32 s8, s4, 0x17700000
	s_addc_u32 s9, s5, 0
	s_add_u32 s8, s8, s0
	s_addc_u32 s9, s9, 0
	s_lshl_b32 s0, s43, 12
	s_add_u32 s98, s8, s0
	s_addc_u32 s99, s9, 0
	s_lshl_b32 s0, s43, 9
	s_add_u32 s0, s0, 0x8000
	s_add_u32 s8, s8, s0
	s_addc_u32 s9, s9, 0
	s_lshl_b32 s0, s43, 11
	s_lshl_b32 s92, s80, 7
	s_add_u32 s0, s0, s92
	s_lshl_b32 s92, s21, 4
	s_add_u32 s0, s0, s92
	v_and_b32_e32 v146, 15, v144
	v_add_u32_e32 v146, s0, v146
	v_lshrrev_b32_e32 v147, 4, v144
	s_lshl_b32 s92, s81, 8
	s_add_u32 s92, s92, 0x700
	v_lshl_add_u32 v148, v147, 4, s92
	v_mov_b32_e32 v149, 0
	s_movk_i32 s93, 0x3000
	v_mad_u64_u32 v[82:83], s[90:91], v146, s93, v[148:149]
	s_add_u32 s90, s4, 0x9f00000
	s_addc_u32 s91, s5, 0
	v_lshl_add_u64 v[82:83], v[82:83], 0, s[90:91]
	global_load_dwordx4 v[2:5], v[82:83], off
	global_load_dwordx4 v[6:9], v[82:83], off offset:64
	global_load_dwordx4 v[10:13], v[82:83], off offset:128
	global_load_dwordx4 v[14:17], v[82:83], off offset:192
	s_lshl_b32 s92, s81, 8
	s_add_u32 s92, s92, 0x400
	v_lshl_add_u32 v148, v147, 3, s92
	v_lshlrev_b32_e32 v150, 11, v146
	v_add_u32_e32 v148, v148, v150
	s_add_u32 s90, s4, 0x1e300000
	s_addc_u32 s91, s5, 0
	v_lshl_add_u64 v[84:85], s[90:91], 0, v[148:149]
	v_mov_b32_e32 v100, 0
	v_mov_b32_e32 v101, 0
	v_mov_b32_e32 v102, 0
	v_mov_b32_e32 v103, 0
	v_mov_b32_e32 v104, 0
	v_mov_b32_e32 v105, 0
	v_mov_b32_e32 v106, 0
	v_mov_b32_e32 v107, 0
	v_mov_b32_e32 v108, 0
	v_mov_b32_e32 v109, 0
	v_mov_b32_e32 v110, 0
	v_mov_b32_e32 v111, 0
	v_mov_b32_e32 v112, 0
	v_mov_b32_e32 v113, 0
	v_mov_b32_e32 v114, 0
	v_mov_b32_e32 v115, 0
	v_mov_b32_e32 v116, 0
	v_mov_b32_e32 v117, 0
	v_mov_b32_e32 v118, 0
	v_mov_b32_e32 v119, 0
	v_mov_b32_e32 v120, 0
	v_mov_b32_e32 v121, 0
	v_mov_b32_e32 v122, 0
	v_mov_b32_e32 v123, 0
	v_mov_b32_e32 v124, 0
	v_mov_b32_e32 v125, 0
	v_mov_b32_e32 v126, 0
	v_mov_b32_e32 v127, 0
	v_mov_b32_e32 v128, 0
	v_mov_b32_e32 v129, 0
	v_mov_b32_e32 v130, 0
	v_mov_b32_e32 v131, 0
	v_mov_b32_e32 v132, 0xf149f2ca
	v_mov_b32_e32 v133, 0xf149f2ca
	v_mov_b32_e32 v134, 0
	v_mov_b32_e32 v135, 0
	s_mov_b32 s89, 0
	s_mov_b32 s42, 36
	s_barrier
	s_cmp_eq_u32 s89, 4
	s_cbranch_scc0 .Lga_nosw1
	s_mov_b64 s[6:7], s[96:97]
	s_mov_b64 s[8:9], s[98:99]

.Lga_loop:
	s_bitcmp1_b32 s101, 0
	s_cbranch_scc1 .Lga_sync0
	s_waitcnt lgkmcnt(0)
	s_bitcmp1_b32 s101, 2
	s_cbranch_scc1 .Lga_qa0
	v_mfma_f32_16x16x32_bf16 v[50:53], v[18:21], v[2:5], 0
	v_mfma_f32_16x16x32_bf16 v[54:57], v[26:29], v[2:5], 0
	v_mfma_f32_16x16x32_bf16 v[58:61], v[34:37], v[2:5], 0
	v_mfma_f32_16x16x32_bf16 v[62:65], v[42:45], v[2:5], 0
	v_mfma_f32_16x16x32_bf16 v[50:53], v[22:25], v[6:9], v[50:53]
	v_mfma_f32_16x16x32_bf16 v[54:57], v[30:33], v[6:9], v[54:57]
	v_mfma_f32_16x16x32_bf16 v[58:61], v[38:41], v[6:9], v[58:61]
	v_mfma_f32_16x16x32_bf16 v[62:65], v[46:49], v[6:9], v[62:65]
.Lga_qa0:
	ds_read_b64 v[168:169], v138 offset:0
	ds_read_b64 v[170:171], v139 offset:0
	ds_read_b64 v[172:173], v140 offset:0
	ds_read_b64 v[174:175], v141 offset:0
	ds_read_b64 v[176:177], v138 offset:2048
	ds_read_b64 v[178:179], v139 offset:2048
	ds_read_b64 v[180:181], v140 offset:2048
	ds_read_b64 v[182:183], v141 offset:2048
	s_bitcmp1_b32 s101, 3
	s_cbranch_scc1 .Lga_qb0
	v_mfma_f32_16x16x32_bf16 v[66:69], v[18:21], v[10:13], 0
	v_mfma_f32_16x16x32_bf16 v[70:73], v[26:29], v[10:13], 0
	v_mfma_f32_16x16x32_bf16 v[74:77], v[34:37], v[10:13], 0
	v_mfma_f32_16x16x32_bf16 v[78:81], v[42:45], v[10:13], 0
	v_mfma_f32_16x16x32_bf16 v[66:69], v[22:25], v[14:17], v[66:69]
	v_mfma_f32_16x16x32_bf16 v[70:73], v[30:33], v[14:17], v[70:73]
	v_mfma_f32_16x16x32_bf16 v[74:77], v[38:41], v[14:17], v[74:77]
	v_mfma_f32_16x16x32_bf16 v[78:81], v[46:49], v[14:17], v[78:81]
.Lga_qb0:
	ds_read_b64 v[184:185], v138 offset:4096
	ds_read_b64 v[186:187], v139 offset:4096
	ds_read_b64 v[188:189], v140 offset:4096
	ds_read_b64 v[190:191], v141 offset:4096
	ds_read_b64 v[192:193], v138 offset:6144
	ds_read_b64 v[194:195], v139 offset:6144
	ds_read_b64 v[196:197], v140 offset:6144
	ds_read_b64 v[198:199], v141 offset:6144
	s_waitcnt lgkmcnt(0)

.Lga_cmp0:
	s_bitcmp1_b32 s101, 0
	s_cbranch_scc1 .Lga_idle0
	s_nop 3
	s_bitcmp1_b32 s101, 2
	s_cbranch_scc1 .Lga_ca0
	v_max3_f32 v144, v50, v51, v52
	v_max3_f32 v145, v53, v54, v55
	v_max3_f32 v150, v56, v57, v58
	v_max3_f32 v151, v59, v60, v61
	v_max3_f32 v152, v62, v63, v64
	v_max3_f32 v144, v144, v145, v65
	v_max3_f32 v144, v144, v150, v151
	v_max_f32_e32 v144, v144, v152
	v_mov_b32_e32 v145, v144
	s_nop 1
	v_permlane16_swap_b32_e32 v144, v145
	v_max_f32_e32 v144, v144, v145
	v_mov_b32_e32 v145, v144
	s_nop 1
	v_permlane32_swap_b32_e32 v144, v145
	v_max_f32_e32 v144, v144, v145
	v_mul_f32_e32 v144, s100, v144
	v_max_f32_e32 v146, v132, v144
	v_cmp_gt_f32_e32 vcc, v146, v132
	s_cbranch_vccz .Lga_nors1
	v_sub_f32_e32 v148, v132, v146
	v_exp_f32_e32 v148, v148
	v_mov_b32_e32 v132, v146
	s_nop 0
	v_mul_f32_e32 v134, v134, v148
	v_pk_mul_f32 v[100:101], v[100:101], v[148:149] op_sel_hi:[1,0]
	v_pk_mul_f32 v[102:103], v[102:103], v[148:149] op_sel_hi:[1,0]
	v_pk_mul_f32 v[104:105], v[104:105], v[148:149] op_sel_hi:[1,0]
	v_pk_mul_f32 v[106:107], v[106:107], v[148:149] op_sel_hi:[1,0]
	v_pk_mul_f32 v[108:109], v[108:109], v[148:149] op_sel_hi:[1,0]
	v_pk_mul_f32 v[110:111], v[110:111], v[148:149] op_sel_hi:[1,0]
	v_pk_mul_f32 v[112:113], v[112:113], v[148:149] op_sel_hi:[1,0]
	v_pk_mul_f32 v[114:115], v[114:115], v[148:149] op_sel_hi:[1,0]

.Lga_ca0:
	s_bitcmp1_b32 s101, 3
	s_cbranch_scc1 .Lga_idle0
	v_max3_f32 v144, v66, v67, v68
	v_max3_f32 v145, v69, v70, v71
	v_max3_f32 v150, v72, v73, v74
	v_max3_f32 v151, v75, v76, v77
	v_max3_f32 v152, v78, v79, v80
	v_max3_f32 v144, v144, v145, v81
	v_max3_f32 v144, v144, v150, v151
	v_max_f32_e32 v144, v144, v152
	v_mov_b32_e32 v145, v144
	s_nop 1
	v_permlane16_swap_b32_e32 v144, v145
	v_max_f32_e32 v144, v144, v145
	v_mov_b32_e32 v145, v144
	s_nop 1
	v_permlane32_swap_b32_e32 v144, v145
	v_max_f32_e32 v144, v144, v145
	v_mul_f32_e32 v144, s100, v144
	v_max_f32_e32 v146, v133, v144
	v_cmp_gt_f32_e32 vcc, v146, v133
	s_cbranch_vccz .Lga_nors2
	v_sub_f32_e32 v148, v133, v146
	v_exp_f32_e32 v148, v148
	v_mov_b32_e32 v133, v146
	s_nop 0
	v_mul_f32_e32 v135, v135, v148
	v_pk_mul_f32 v[116:117], v[116:117], v[148:149] op_sel_hi:[1,0]
	v_pk_mul_f32 v[118:119], v[118:119], v[148:149] op_sel_hi:[1,0]
	v_pk_mul_f32 v[120:121], v[120:121], v[148:149] op_sel_hi:[1,0]
	v_pk_mul_f32 v[122:123], v[122:123], v[148:149] op_sel_hi:[1,0]
	v_pk_mul_f32 v[124:125], v[124:125], v[148:149] op_sel_hi:[1,0]
	v_pk_mul_f32 v[126:127], v[126:127], v[148:149] op_sel_hi:[1,0]
	v_pk_mul_f32 v[128:129], v[128:129], v[148:149] op_sel_hi:[1,0]
	v_pk_mul_f32 v[130:131], v[130:131], v[148:149] op_sel_hi:[1,0]

.Lga_idle0:
	s_sub_u32 s42, s42, 1
	s_bitcmp1_b32 s101, 0
	s_cbranch_scc1 .Lga_sync1
	s_waitcnt lgkmcnt(0)
	s_bitcmp1_b32 s101, 2
	s_cbranch_scc1 .Lga_qa1
	v_mfma_f32_16x16x32_bf16 v[50:53], v[18:21], v[2:5], 0
	v_mfma_f32_16x16x32_bf16 v[54:57], v[26:29], v[2:5], 0
	v_mfma_f32_16x16x32_bf16 v[58:61], v[34:37], v[2:5], 0
	v_mfma_f32_16x16x32_bf16 v[62:65], v[42:45], v[2:5], 0
	v_mfma_f32_16x16x32_bf16 v[50:53], v[22:25], v[6:9], v[50:53]
	v_mfma_f32_16x16x32_bf16 v[54:57], v[30:33], v[6:9], v[54:57]
	v_mfma_f32_16x16x32_bf16 v[58:61], v[38:41], v[6:9], v[58:61]
	v_mfma_f32_16x16x32_bf16 v[62:65], v[46:49], v[6:9], v[62:65]
.Lga_qa1:
	ds_read_b64 v[168:169], v138 offset:16384
	ds_read_b64 v[170:171], v139 offset:16384
	ds_read_b64 v[172:173], v140 offset:16384
	ds_read_b64 v[174:175], v141 offset:16384
	ds_read_b64 v[176:177], v138 offset:18432
	ds_read_b64 v[178:179], v139 offset:18432
	ds_read_b64 v[180:181], v140 offset:18432
	ds_read_b64 v[182:183], v141 offset:18432
	s_bitcmp1_b32 s101, 3
	s_cbranch_scc1 .Lga_qb1
	v_mfma_f32_16x16x32_bf16 v[66:69], v[18:21], v[10:13], 0
	v_mfma_f32_16x16x32_bf16 v[70:73], v[26:29], v[10:13], 0
	v_mfma_f32_16x16x32_bf16 v[74:77], v[34:37], v[10:13], 0
	v_mfma_f32_16x16x32_bf16 v[78:81], v[42:45], v[10:13], 0
	v_mfma_f32_16x16x32_bf16 v[66:69], v[22:25], v[14:17], v[66:69]
	v_mfma_f32_16x16x32_bf16 v[70:73], v[30:33], v[14:17], v[70:73]
	v_mfma_f32_16x16x32_bf16 v[74:77], v[38:41], v[14:17], v[74:77]
	v_mfma_f32_16x16x32_bf16 v[78:81], v[46:49], v[14:17], v[78:81]
.Lga_qb1:
	ds_read_b64 v[184:185], v138 offset:20480
	ds_read_b64 v[186:187], v139 offset:20480
	ds_read_b64 v[188:189], v140 offset:20480
	ds_read_b64 v[190:191], v141 offset:20480
	ds_read_b64 v[192:193], v138 offset:22528
	ds_read_b64 v[194:195], v139 offset:22528
	ds_read_b64 v[196:197], v140 offset:22528
	ds_read_b64 v[198:199], v141 offset:22528
	s_waitcnt lgkmcnt(0)

.Lga_qa2:
	ds_read_b64 v[168:169], v138 offset:32768
	ds_read_b64 v[170:171], v139 offset:32768
	ds_read_b64 v[172:173], v140 offset:32768
	ds_read_b64 v[174:175], v141 offset:32768
	ds_read_b64 v[176:177], v138 offset:34816
	ds_read_b64 v[178:179], v139 offset:34816
	ds_read_b64 v[180:181], v140 offset:34816
	ds_read_b64 v[182:183], v141 offset:34816
	s_bitcmp1_b32 s101, 3
	s_cbranch_scc1 .Lga_qb2
	v_mfma_f32_16x16x32_bf16 v[66:69], v[18:21], v[10:13], 0
	v_mfma_f32_16x16x32_bf16 v[70:73], v[26:29], v[10:13], 0
	v_mfma_f32_16x16x32_bf16 v[74:77], v[34:37], v[10:13], 0
	v_mfma_f32_16x16x32_bf16 v[78:81], v[42:45], v[10:13], 0
	v_mfma_f32_16x16x32_bf16 v[66:69], v[22:25], v[14:17], v[66:69]
	v_mfma_f32_16x16x32_bf16 v[70:73], v[30:33], v[14:17], v[70:73]
	v_mfma_f32_16x16x32_bf16 v[74:77], v[38:41], v[14:17], v[74:77]
	v_mfma_f32_16x16x32_bf16 v[78:81], v[46:49], v[14:17], v[78:81]
.Lga_qb2:
	ds_read_b64 v[184:185], v138 offset:36864
	ds_read_b64 v[186:187], v139 offset:36864
	ds_read_b64 v[188:189], v140 offset:36864
	ds_read_b64 v[190:191], v141 offset:36864
	ds_read_b64 v[192:193], v138 offset:38912
	ds_read_b64 v[194:195], v139 offset:38912
	ds_read_b64 v[196:197], v140 offset:38912
	ds_read_b64 v[198:199], v141 offset:38912
	s_waitcnt lgkmcnt(0)

.Lga_qa3:
	ds_read_b64 v[168:169], v138 offset:49152
	ds_read_b64 v[170:171], v139 offset:49152
	ds_read_b64 v[172:173], v140 offset:49152
	ds_read_b64 v[174:175], v141 offset:49152
	ds_read_b64 v[176:177], v138 offset:51200
	ds_read_b64 v[178:179], v139 offset:51200
	ds_read_b64 v[180:181], v140 offset:51200
	ds_read_b64 v[182:183], v141 offset:51200
	s_bitcmp1_b32 s101, 3
	s_cbranch_scc1 .Lga_qb3
	v_mfma_f32_16x16x32_bf16 v[66:69], v[18:21], v[10:13], 0
	v_mfma_f32_16x16x32_bf16 v[70:73], v[26:29], v[10:13], 0
	v_mfma_f32_16x16x32_bf16 v[74:77], v[34:37], v[10:13], 0
	v_mfma_f32_16x16x32_bf16 v[78:81], v[42:45], v[10:13], 0
	v_mfma_f32_16x16x32_bf16 v[66:69], v[22:25], v[14:17], v[66:69]
	v_mfma_f32_16x16x32_bf16 v[70:73], v[30:33], v[14:17], v[70:73]
	v_mfma_f32_16x16x32_bf16 v[74:77], v[38:41], v[14:17], v[74:77]
	v_mfma_f32_16x16x32_bf16 v[78:81], v[46:49], v[14:17], v[78:81]
.Lga_qb3:
	ds_read_b64 v[184:185], v138 offset:53248
	ds_read_b64 v[186:187], v139 offset:53248
	ds_read_b64 v[188:189], v140 offset:53248
	ds_read_b64 v[190:191], v141 offset:53248
	ds_read_b64 v[192:193], v138 offset:55296
	ds_read_b64 v[194:195], v139 offset:55296
	ds_read_b64 v[196:197], v140 offset:55296
	ds_read_b64 v[198:199], v141 offset:55296
	s_waitcnt lgkmcnt(0)

.Lga_idle3:
	s_sub_u32 s42, s42, 1
	s_cmp_eq_u32 s42, 0
	s_cbranch_scc0 .Lga_loop
	s_bitcmp1_b32 s101, 0
	s_cbranch_scc1 .Lga_nostore
	s_nop 7
	s_nop 1
	s_bitcmp1_b32 s101, 2
	s_cbranch_scc1 .Lga_fin0
	v_mov_b32_e32 v145, v134
	s_nop 1
	v_permlane16_swap_b32_e32 v134, v145
	v_add_f32_e32 v134, v134, v145
	v_mov_b32_e32 v145, v134
	s_nop 1
	v_permlane32_swap_b32_e32 v134, v145
	v_add_f32_e32 v134, v134, v145
	v_rcp_f32_e32 v134, v134
	s_nop 0
	v_mul_f32_e32 v100, v100, v134
	v_mul_f32_e32 v101, v101, v134
	v_mul_f32_e32 v102, v102, v134
	v_mul_f32_e32 v103, v103, v134
	v_mul_f32_e32 v104, v104, v134
	v_mul_f32_e32 v105, v105, v134
	v_mul_f32_e32 v106, v106, v134
	v_mul_f32_e32 v107, v107, v134
	v_mul_f32_e32 v108, v108, v134
	v_mul_f32_e32 v109, v109, v134
	v_mul_f32_e32 v110, v110, v134
	v_mul_f32_e32 v111, v111, v134
	v_mul_f32_e32 v112, v112, v134
	v_mul_f32_e32 v113, v113, v134
	v_mul_f32_e32 v114, v114, v134
	v_mul_f32_e32 v115, v115, v134
	v_cvt_pk_bf16_f32 v146, v100, v101
	v_cvt_pk_bf16_f32 v147, v102, v103
	v_cvt_pk_bf16_f32 v148, v104, v105
	v_cvt_pk_bf16_f32 v149, v106, v107
	v_cvt_pk_bf16_f32 v150, v108, v109
	v_cvt_pk_bf16_f32 v151, v110, v111
	v_cvt_pk_bf16_f32 v152, v112, v113
	v_cvt_pk_bf16_f32 v153, v114, v115
	global_store_dwordx2 v[84:85], v[146:147], off offset:0
	global_store_dwordx2 v[84:85], v[148:149], off offset:32
	global_store_dwordx2 v[84:85], v[150:151], off offset:64
	global_store_dwordx2 v[84:85], v[152:153], off offset:96
.Lga_fin0:
	s_bitcmp1_b32 s101, 3
	s_cbranch_scc1 .Lga_fin1
	v_mov_b32_e32 v145, v135
	s_nop 1
	v_permlane16_swap_b32_e32 v135, v145
	v_add_f32_e32 v135, v135, v145
	v_mov_b32_e32 v145, v135
	s_nop 1
	v_permlane32_swap_b32_e32 v135, v145
	v_add_f32_e32 v135, v135, v145
	v_rcp_f32_e32 v135, v135
	s_nop 0
	v_mul_f32_e32 v116, v116, v135
	v_mul_f32_e32 v117, v117, v135
	v_mul_f32_e32 v118, v118, v135
	v_mul_f32_e32 v119, v119, v135
	v_mul_f32_e32 v120, v120, v135
	v_mul_f32_e32 v121, v121, v135
	v_mul_f32_e32 v122, v122, v135
	v_mul_f32_e32 v123, v123, v135
	v_mul_f32_e32 v124, v124, v135
	v_mul_f32_e32 v125, v125, v135
	v_mul_f32_e32 v126, v126, v135
	v_mul_f32_e32 v127, v127, v135
	v_mul_f32_e32 v128, v128, v135
	v_mul_f32_e32 v129, v129, v135
	v_mul_f32_e32 v130, v130, v135
	v_mul_f32_e32 v131, v131, v135
	v_cvt_pk_bf16_f32 v146, v116, v117
	v_cvt_pk_bf16_f32 v147, v118, v119
	v_cvt_pk_bf16_f32 v148, v120, v121
	v_cvt_pk_bf16_f32 v149, v122, v123
	v_cvt_pk_bf16_f32 v150, v124, v125
	v_cvt_pk_bf16_f32 v151, v126, v127
	v_cvt_pk_bf16_f32 v152, v128, v129
	v_cvt_pk_bf16_f32 v153, v130, v131
	global_store_dwordx2 v[84:85], v[146:147], off offset:128
	global_store_dwordx2 v[84:85], v[148:149], off offset:160
	global_store_dwordx2 v[84:85], v[150:151], off offset:192
	global_store_dwordx2 v[84:85], v[152:153], off offset:224
.Lga_fin1:
.Lga_nostore:
	s_bitcmp1_b32 s101, 1
	s_cbranch_scc1 .Lga_done
	s_add_u32 s1, s1, 0x70
	s_cmpk_lt_u32 s1, 0xe0
	s_cbranch_scc1 .Lga_unit
